# static s_setprio 1 for waves 4-7 around the GEMM main loop, per-segment setprio flips removed
# speedup vs baseline: 1.0140x; 1.0127x over previous
; #define PG8_STAGE(bufoff, gbase, voff) do { _Pragma("unroll") for (int _i = 0; _i < 2; ++_i) \
;         __builtin_amdgcn_global_load_lds((const unsigned*)((const char*)(gbase) + (voff)[_i]), (LAS unsigned*)(lds + (bufoff) + ldsw + _i * 8192), 16, 0, 0); } while (0)
; #define PG8_LDA(dst, b, h) do { _Pragma("unroll") for (int m = 0; m < 4; ++m) _Pragma("unroll") for (int k = 0; k < 2; ++k) dst[m][k] = *(const LAS bf16x8*)(lds + PG8_SA(b, h) + aoff + m * 2048 + k * 1024); } while (0)
; #define PG8_LDB(dst, b, h) do { _Pragma("unroll") for (int n = 0; n < 2; ++n) _Pragma("unroll") for (int k = 0; k < 2; ++k) dst[n][k] = *(const LAS bf16x8*)(lds + PG8_SB(b, h) + boff + n * 2048 + k * 1024); } while (0)
; #define PG8_MMA(ai, bj, At, Bt) do { __builtin_amdgcn_s_setprio(1); _Pragma("unroll") for (int m = 0; m < 4; ++m) _Pragma("unroll") for (int n = 0; n < 2; ++n) _Pragma("unroll") for (int k = 0; k < 2; ++k) \
;         acc[ai][bj][m][n] = __builtin_amdgcn_mfma_f32_16x16x32_bf16(Bt[n][k], At[m][k], acc[ai][bj][m][n], 0, 0, 0); __builtin_amdgcn_s_setprio(0); } while (0)
; #define PG8_WAIT_V(n) asm volatile("s_waitcnt vmcnt(" #n ")" ::: "memory")
; #define PG8_WAIT_L(n) asm volatile("s_waitcnt lgkmcnt(" #n ")" ::: "memory")
; #define PG8_BAR __builtin_amdgcn_s_barrier()
; __device__ __forceinline__ void gemm_phase(LAS unsigned char* lds, const GemmD g, const Sched& S, const Epi& E) {
;     ...
;         for (int t = 0; t < nt; t += 2) {
;             const bool last = (t == nt - 2);
;             const char* a1 = cA + (size_t)(t + 1) * kstep;
;             const char* a2 = last ? nA : cA + (size_t)(t + 2) * kstep; const char* b2 = last ? nB : cB + (size_t)(t + 2) * kstep;
;             const char* a3 = a2 + kstep; const char* b3 = b2 + kstep;
;             PG8_LDB(B0, 0, 0); PG8_LDB(B1, 0, 1); PG8_SCHED; PG8_LDA(At, 0, 0); PG8_STAGE(PG8_SA(1, 1), a1 + hstepA, voffA);
;             PG8_WAIT_V(8); PG8_WAIT_L(0); PG8_BAR; PG8_MMA(0, 0, At, B0); PG8_MMA(0, 1, At, B1); PG8_BAR; PG8_SCHED;
;     ...
; #pragma unroll
;         for (int a = 0; a < 2; ++a)
; #pragma unroll
;             for (int b = 0; b < 2; ++b)
; #pragma unroll
;                 for (int m = 0; m < 4; ++m)
; #pragma unroll
;                     for (int n = 0; n < 2; ++n) acc[a][b][m][n] = (f32x4){0.f, 0.f, 0.f, 0.f};
;         cur = nxt; cA = nA; cB = nB; ++ui;
;         if (wr == 1) PG8_BAR;
.LBB0_214:
	s_add_u32 s8, s8, 0x80
	s_addc_u32 s9, s9, 0
	s_add_u32 s34, s26, 0x100
	v_mov_b32_e32 v2, 0
	s_addc_u32 s35, s27, 0
	s_mov_b32 s26, 0
	v_mov_b32_e32 v3, v2
	v_mov_b32_e32 v4, v2
	v_mov_b32_e32 v5, v2
	v_mov_b32_e32 v6, v2
	v_mov_b32_e32 v7, v2
	v_mov_b32_e32 v8, v2
	v_mov_b32_e32 v9, v2
	v_mov_b32_e32 v18, v2
	v_mov_b32_e32 v19, v2
	v_mov_b32_e32 v20, v2
	v_mov_b32_e32 v21, v2
	v_mov_b32_e32 v22, v2
	v_mov_b32_e32 v23, v2
	v_mov_b32_e32 v24, v2
	v_mov_b32_e32 v25, v2
	v_mov_b32_e32 v34, v2
	v_mov_b32_e32 v35, v2
	v_mov_b32_e32 v36, v2
	v_mov_b32_e32 v37, v2
	v_mov_b32_e32 v38, v2
	v_mov_b32_e32 v39, v2
	v_mov_b32_e32 v40, v2
	v_mov_b32_e32 v41, v2
	v_mov_b32_e32 v50, v2
	v_mov_b32_e32 v51, v2
	v_mov_b32_e32 v52, v2
	v_mov_b32_e32 v53, v2
	v_mov_b32_e32 v54, v2
	v_mov_b32_e32 v55, v2
	v_mov_b32_e32 v56, v2
	v_mov_b32_e32 v57, v2
	v_mov_b32_e32 v10, v2
	v_mov_b32_e32 v11, v2
	v_mov_b32_e32 v12, v2
	v_mov_b32_e32 v13, v2
	v_mov_b32_e32 v14, v2
	v_mov_b32_e32 v15, v2
	v_mov_b32_e32 v16, v2
	v_mov_b32_e32 v17, v2
	v_mov_b32_e32 v26, v2
	v_mov_b32_e32 v27, v2
	v_mov_b32_e32 v28, v2
	v_mov_b32_e32 v29, v2
	v_mov_b32_e32 v30, v2
	v_mov_b32_e32 v31, v2
	v_mov_b32_e32 v32, v2
	v_mov_b32_e32 v33, v2
	v_mov_b32_e32 v42, v2
	v_mov_b32_e32 v43, v2
	v_mov_b32_e32 v44, v2
	v_mov_b32_e32 v45, v2
	v_mov_b32_e32 v46, v2
	v_mov_b32_e32 v47, v2
	v_mov_b32_e32 v48, v2
	v_mov_b32_e32 v49, v2
	v_mov_b32_e32 v58, v2
	v_mov_b32_e32 v59, v2
	v_mov_b32_e32 v60, v2
	v_mov_b32_e32 v61, v2
	v_mov_b32_e32 v62, v2
	v_mov_b32_e32 v63, v2
	v_mov_b32_e32 v64, v2
	v_mov_b32_e32 v65, v2
	v_mov_b32_e32 v66, v2
	v_mov_b32_e32 v67, v2
	v_mov_b32_e32 v68, v2
	v_mov_b32_e32 v69, v2
	v_mov_b32_e32 v70, v2
	v_mov_b32_e32 v71, v2
	v_mov_b32_e32 v72, v2
	v_mov_b32_e32 v73, v2
	v_mov_b32_e32 v82, v2
	v_mov_b32_e32 v83, v2
	v_mov_b32_e32 v84, v2
	v_mov_b32_e32 v85, v2
	v_mov_b32_e32 v86, v2
	v_mov_b32_e32 v87, v2
	v_mov_b32_e32 v88, v2
	v_mov_b32_e32 v89, v2
	v_mov_b32_e32 v98, v2
	v_mov_b32_e32 v99, v2
	v_mov_b32_e32 v100, v2
	v_mov_b32_e32 v101, v2
	v_mov_b32_e32 v102, v2
	v_mov_b32_e32 v103, v2
	v_mov_b32_e32 v104, v2
	v_mov_b32_e32 v105, v2
	v_mov_b32_e32 v114, v2
	v_mov_b32_e32 v115, v2
	v_mov_b32_e32 v116, v2
	v_mov_b32_e32 v117, v2
	v_mov_b32_e32 v118, v2
	v_mov_b32_e32 v119, v2
	v_mov_b32_e32 v120, v2
	v_mov_b32_e32 v121, v2
	v_mov_b32_e32 v74, v2
	v_mov_b32_e32 v75, v2
	v_mov_b32_e32 v76, v2
	v_mov_b32_e32 v77, v2
	v_mov_b32_e32 v78, v2
	v_mov_b32_e32 v79, v2
	v_mov_b32_e32 v80, v2
	v_mov_b32_e32 v81, v2
	v_mov_b32_e32 v90, v2
	v_mov_b32_e32 v91, v2
	v_mov_b32_e32 v92, v2
	v_mov_b32_e32 v93, v2
	v_mov_b32_e32 v94, v2
	v_mov_b32_e32 v95, v2
	v_mov_b32_e32 v96, v2
	v_mov_b32_e32 v97, v2
	v_mov_b32_e32 v106, v2
	v_mov_b32_e32 v107, v2
	v_mov_b32_e32 v108, v2
	v_mov_b32_e32 v109, v2
	v_mov_b32_e32 v110, v2
	v_mov_b32_e32 v111, v2
	v_mov_b32_e32 v112, v2
	v_mov_b32_e32 v113, v2
	v_mov_b32_e32 v122, v2
	v_mov_b32_e32 v123, v2
	v_mov_b32_e32 v124, v2
	v_mov_b32_e32 v125, v2
	v_mov_b32_e32 v126, v2
	v_mov_b32_e32 v127, v2
	v_mov_b32_e32 v128, v2
	v_mov_b32_e32 v129, v2
	v_readlane_b32 s22, v250, 17
	s_cmp_lg_u32 s22, 0
	s_cbranch_scc0 .Lprio_done
	s_setprio 1
.Lprio_done:
.LBB0_215:
	s_add_i32 s92, s26, 2
	s_add_u32 s93, s8, 0x80
	s_addc_u32 s27, s9, 0
	s_add_i32 s22, 0, 0x10000
	s_cmp_eq_u32 s11, s26
	s_cselect_b32 s27, s1, s27
	s_cselect_b32 s26, s0, s93
	v_add_u32_e32 v0, s22, v160
	s_cselect_b32 vcc_hi, s17, s35
	s_cselect_b32 vcc_lo, s16, s34
	s_add_i32 s23, 0, 0x14000
	ds_read_b128 v[130:133], v0
	ds_read_b128 v[146:149], v0 offset:1024
	ds_read_b128 v[150:153], v0 offset:2048
	ds_read_b128 v[154:157], v0 offset:3072
	v_add_u32_e32 v0, s23, v160
	ds_read_b128 v[162:165], v0
	ds_read_b128 v[166:169], v0 offset:1024
	ds_read_b128 v[170:173], v0 offset:2048
	ds_read_b128 v[174:177], v0 offset:3072
	v_lshl_add_u64 v[178:179], s[8:9], 0, v[142:143]
	s_add_i32 m0, s31, 0xc000
	ds_read_b128 v[182:185], v161
	ds_read_b128 v[186:189], v161 offset:1024
	ds_read_b128 v[190:193], v161 offset:2048
	ds_read_b128 v[216:219], v161 offset:3072
	ds_read_b128 v[220:223], v161 offset:4096
	ds_read_b128 v[224:227], v161 offset:5120
	ds_read_b128 v[228:231], v161 offset:6144
	ds_read_b128 v[236:239], v161 offset:7168
	global_load_lds_dwordx4 v[178:179], off
	v_lshl_add_u64 v[178:179], s[8:9], 0, v[144:145]
	s_add_i32 m0, s31, 0xe000
	s_nop 0
	global_load_lds_dwordx4 v[178:179], off
	s_waitcnt vmcnt(8)
	s_waitcnt lgkmcnt(0)
	s_barrier
	s_waitcnt lgkmcnt(0)
	v_mfma_f32_16x16x32_bf16 v[126:129], v[130:133], v[182:185], v[126:129]
	v_mfma_f32_16x16x32_bf16 v[122:125], v[150:153], v[182:185], v[122:125]
	v_mfma_f32_16x16x32_bf16 v[110:113], v[130:133], v[190:193], v[110:113]
	v_mfma_f32_16x16x32_bf16 v[106:109], v[150:153], v[190:193], v[106:109]
	v_mfma_f32_16x16x32_bf16 v[94:97], v[130:133], v[220:223], v[94:97]
	v_mfma_f32_16x16x32_bf16 v[90:93], v[150:153], v[220:223], v[90:93]
	v_mfma_f32_16x16x32_bf16 v[78:81], v[130:133], v[228:231], v[78:81]
	v_mfma_f32_16x16x32_bf16 v[74:77], v[150:153], v[228:231], v[74:77]
	v_mfma_f32_16x16x32_bf16 v[126:129], v[146:149], v[186:189], v[126:129]
	v_mfma_f32_16x16x32_bf16 v[122:125], v[154:157], v[186:189], v[122:125]
	v_mfma_f32_16x16x32_bf16 v[110:113], v[146:149], v[216:219], v[110:113]
	v_mfma_f32_16x16x32_bf16 v[106:109], v[154:157], v[216:219], v[106:109]
	v_mfma_f32_16x16x32_bf16 v[94:97], v[146:149], v[224:227], v[94:97]
	v_mfma_f32_16x16x32_bf16 v[90:93], v[154:157], v[224:227], v[90:93]
	v_mfma_f32_16x16x32_bf16 v[78:81], v[146:149], v[236:239], v[78:81]
	v_mfma_f32_16x16x32_bf16 v[74:77], v[154:157], v[236:239], v[74:77]
	v_mfma_f32_16x16x32_bf16 v[118:121], v[162:165], v[182:185], v[118:121]
	v_mfma_f32_16x16x32_bf16 v[114:117], v[170:173], v[182:185], v[114:117]
	v_mfma_f32_16x16x32_bf16 v[102:105], v[162:165], v[190:193], v[102:105]
	v_mfma_f32_16x16x32_bf16 v[98:101], v[170:173], v[190:193], v[98:101]
	v_mfma_f32_16x16x32_bf16 v[86:89], v[162:165], v[220:223], v[86:89]
	v_mfma_f32_16x16x32_bf16 v[82:85], v[170:173], v[220:223], v[82:85]
	v_mfma_f32_16x16x32_bf16 v[70:73], v[162:165], v[228:231], v[70:73]
	v_mfma_f32_16x16x32_bf16 v[66:69], v[170:173], v[228:231], v[66:69]
	v_mfma_f32_16x16x32_bf16 v[118:121], v[166:169], v[186:189], v[118:121]
	v_mfma_f32_16x16x32_bf16 v[114:117], v[174:177], v[186:189], v[114:117]
	v_mfma_f32_16x16x32_bf16 v[102:105], v[166:169], v[216:219], v[102:105]
	v_mfma_f32_16x16x32_bf16 v[98:101], v[174:177], v[216:219], v[98:101]
	v_mfma_f32_16x16x32_bf16 v[86:89], v[166:169], v[224:227], v[86:89]
	v_mfma_f32_16x16x32_bf16 v[82:85], v[174:177], v[224:227], v[82:85]
	v_mfma_f32_16x16x32_bf16 v[70:73], v[166:169], v[236:239], v[70:73]
	v_mfma_f32_16x16x32_bf16 v[66:69], v[174:177], v[236:239], v[66:69]
	s_barrier
; #define PG8_STAGE(bufoff, gbase, voff) do { _Pragma("unroll") for (int _i = 0; _i < 2; ++_i) \
;         __builtin_amdgcn_global_load_lds((const unsigned*)((const char*)(gbase) + (voff)[_i]), (LAS unsigned*)(lds + (bufoff) + ldsw + _i * 8192), 16, 0, 0); } while (0)
; #define PG8_LDA(dst, b, h) do { _Pragma("unroll") for (int m = 0; m < 4; ++m) _Pragma("unroll") for (int k = 0; k < 2; ++k) dst[m][k] = *(const LAS bf16x8*)(lds + PG8_SA(b, h) + aoff + m * 2048 + k * 1024); } while (0)
; #define PG8_LDB(dst, b, h) do { _Pragma("unroll") for (int n = 0; n < 2; ++n) _Pragma("unroll") for (int k = 0; k < 2; ++k) dst[n][k] = *(const LAS bf16x8*)(lds + PG8_SB(b, h) + boff + n * 2048 + k * 1024); } while (0)
; #define PG8_MMA(ai, bj, At, Bt) do { __builtin_amdgcn_s_setprio(1); _Pragma("unroll") for (int m = 0; m < 4; ++m) _Pragma("unroll") for (int n = 0; n < 2; ++n) _Pragma("unroll") for (int k = 0; k < 2; ++k) \
;         acc[ai][bj][m][n] = __builtin_amdgcn_mfma_f32_16x16x32_bf16(Bt[n][k], At[m][k], acc[ai][bj][m][n], 0, 0, 0); __builtin_amdgcn_s_setprio(0); } while (0)
; #define PG8_WAIT_V(n) asm volatile("s_waitcnt vmcnt(" #n ")" ::: "memory")
; #define PG8_WAIT_L(n) asm volatile("s_waitcnt lgkmcnt(" #n ")" ::: "memory")
; #define PG8_BAR __builtin_amdgcn_s_barrier()
; #define PG8_SCHED __builtin_amdgcn_sched_barrier(0)
; __device__ __forceinline__ void gemm_phase(LAS unsigned char* lds, const GemmD g, const Sched& S, const Epi& E) {
;     ...
;             PG8_LDA(At, 0, 1); PG8_STAGE(PG8_SB(0, 0), b2, voffB); PG8_STAGE(PG8_SB(0, 1), b2 + hstepB, voffB); PG8_STAGE(PG8_SA(0, 0), a2, voffA);
;             PG8_WAIT_V(8); PG8_WAIT_L(0); PG8_BAR; PG8_MMA(1, 0, At, B0); PG8_MMA(1, 1, At, B1); PG8_BAR; PG8_SCHED;
;             PG8_LDB(B0, 1, 0); PG8_LDB(B1, 1, 1); PG8_SCHED; PG8_LDA(At, 1, 0); PG8_STAGE(PG8_SA(0, 1), a2 + hstepA, voffA);
;             PG8_WAIT_V(8); PG8_WAIT_L(0); PG8_BAR; PG8_MMA(0, 0, At, B0); PG8_MMA(0, 1, At, B1); PG8_BAR; PG8_SCHED;
	s_add_i32 s22, s22, s30
	v_lshl_add_u64 v[178:179], vcc, 0, v[136:137]
	s_mov_b32 m0, s22
	ds_read_b128 v[182:185], v161 offset:16384
	ds_read_b128 v[186:189], v161 offset:17408
	ds_read_b128 v[190:193], v161 offset:18432
	ds_read_b128 v[216:219], v161 offset:19456
	ds_read_b128 v[220:223], v161 offset:20480
	ds_read_b128 v[224:227], v161 offset:21504
	ds_read_b128 v[228:231], v161 offset:22528
	ds_read_b128 v[236:239], v161 offset:23552
	global_load_lds_dwordx4 v[178:179], off
	s_add_i32 m0, s22, 0x2000
	v_lshl_add_u64 v[194:195], vcc, 0, v[140:141]
	s_add_u32 vcc_lo, vcc_lo, s29
	s_addc_u32 vcc_hi, vcc_hi, 0
	s_add_i32 s22, s23, s30
	global_load_lds_dwordx4 v[194:195], off
	v_lshl_add_u64 v[240:241], vcc, 0, v[136:137]
	s_mov_b32 m0, s22
	v_lshl_add_u64 v[242:243], vcc, 0, v[140:141]
	global_load_lds_dwordx4 v[240:241], off
	s_add_i32 m0, s22, 0x2000
	v_lshl_add_u64 v[244:245], s[26:27], 0, v[134:135]
	global_load_lds_dwordx4 v[242:243], off
	s_mov_b32 m0, s31
	v_lshl_add_u64 v[246:247], s[26:27], 0, v[138:139]
	global_load_lds_dwordx4 v[244:245], off
	s_mov_b32 m0, s14
	s_nop 0
	global_load_lds_dwordx4 v[246:247], off
	s_waitcnt vmcnt(8)
	s_waitcnt lgkmcnt(0)
	s_barrier
	s_waitcnt lgkmcnt(0)
	v_mfma_f32_16x16x32_bf16 v[62:65], v[130:133], v[182:185], v[62:65]
	v_mfma_f32_16x16x32_bf16 v[58:61], v[150:153], v[182:185], v[58:61]
	v_mfma_f32_16x16x32_bf16 v[46:49], v[130:133], v[190:193], v[46:49]
	v_mfma_f32_16x16x32_bf16 v[42:45], v[150:153], v[190:193], v[42:45]
	v_mfma_f32_16x16x32_bf16 v[30:33], v[130:133], v[220:223], v[30:33]
	v_mfma_f32_16x16x32_bf16 v[26:29], v[150:153], v[220:223], v[26:29]
	v_mfma_f32_16x16x32_bf16 v[14:17], v[130:133], v[228:231], v[14:17]
	v_mfma_f32_16x16x32_bf16 v[10:13], v[150:153], v[228:231], v[10:13]
	v_mfma_f32_16x16x32_bf16 v[62:65], v[146:149], v[186:189], v[62:65]
	v_mfma_f32_16x16x32_bf16 v[58:61], v[154:157], v[186:189], v[58:61]
	v_mfma_f32_16x16x32_bf16 v[46:49], v[146:149], v[216:219], v[46:49]
	v_mfma_f32_16x16x32_bf16 v[42:45], v[154:157], v[216:219], v[42:45]
	v_mfma_f32_16x16x32_bf16 v[30:33], v[146:149], v[224:227], v[30:33]
	v_mfma_f32_16x16x32_bf16 v[26:29], v[154:157], v[224:227], v[26:29]
	v_mfma_f32_16x16x32_bf16 v[14:17], v[146:149], v[236:239], v[14:17]
	v_mfma_f32_16x16x32_bf16 v[10:13], v[154:157], v[236:239], v[10:13]
	v_mfma_f32_16x16x32_bf16 v[54:57], v[162:165], v[182:185], v[54:57]
	v_mfma_f32_16x16x32_bf16 v[50:53], v[170:173], v[182:185], v[50:53]
	v_mfma_f32_16x16x32_bf16 v[38:41], v[162:165], v[190:193], v[38:41]
	v_mfma_f32_16x16x32_bf16 v[34:37], v[170:173], v[190:193], v[34:37]
	v_mfma_f32_16x16x32_bf16 v[22:25], v[162:165], v[220:223], v[22:25]
	v_mfma_f32_16x16x32_bf16 v[18:21], v[170:173], v[220:223], v[18:21]
	v_mfma_f32_16x16x32_bf16 v[6:9], v[162:165], v[228:231], v[6:9]
	v_mfma_f32_16x16x32_bf16 v[2:5], v[170:173], v[228:231], v[2:5]
	v_mfma_f32_16x16x32_bf16 v[54:57], v[166:169], v[186:189], v[54:57]
	v_mfma_f32_16x16x32_bf16 v[50:53], v[174:177], v[186:189], v[50:53]
	v_mfma_f32_16x16x32_bf16 v[38:41], v[166:169], v[216:219], v[38:41]
	v_mfma_f32_16x16x32_bf16 v[34:37], v[174:177], v[216:219], v[34:37]
	v_mfma_f32_16x16x32_bf16 v[22:25], v[166:169], v[224:227], v[22:25]
	v_mfma_f32_16x16x32_bf16 v[18:21], v[174:177], v[224:227], v[18:21]
	v_mfma_f32_16x16x32_bf16 v[6:9], v[166:169], v[236:239], v[6:9]
	v_mfma_f32_16x16x32_bf16 v[2:5], v[174:177], v[236:239], v[2:5]
	s_barrier
	s_add_i32 s22, 0, 0x18000
	v_add_u32_e32 v0, s22, v160
	s_add_i32 s23, 0, 0x1c000
	ds_read_b128 v[130:133], v0
	ds_read_b128 v[146:149], v0 offset:1024
	ds_read_b128 v[150:153], v0 offset:2048
	ds_read_b128 v[154:157], v0 offset:3072
	v_add_u32_e32 v0, s23, v160
	ds_read_b128 v[162:165], v0
	ds_read_b128 v[166:169], v0 offset:1024
	ds_read_b128 v[170:173], v0 offset:2048
	ds_read_b128 v[174:177], v0 offset:3072
	s_add_u32 s26, s26, s94
	s_addc_u32 s27, s27, 0
	s_mov_b32 m0, s15
	v_lshl_add_u64 v[248:249], s[26:27], 0, v[134:135]
	ds_read_b128 v[182:185], v161 offset:32768
	ds_read_b128 v[186:189], v161 offset:33792
	ds_read_b128 v[190:193], v161 offset:34816
	ds_read_b128 v[216:219], v161 offset:35840
	ds_read_b128 v[220:223], v161 offset:36864
	ds_read_b128 v[224:227], v161 offset:37888
	ds_read_b128 v[228:231], v161 offset:38912
	ds_read_b128 v[236:239], v161 offset:39936
	global_load_lds_dwordx4 v[248:249], off
	v_lshl_add_u64 v[248:249], s[26:27], 0, v[138:139]
	s_mov_b32 m0, s10
	s_nop 0
	global_load_lds_dwordx4 v[248:249], off
	s_waitcnt vmcnt(8)
	s_waitcnt lgkmcnt(0)
	s_barrier
; #define PG8_STAGE(bufoff, gbase, voff) do { _Pragma("unroll") for (int _i = 0; _i < 2; ++_i) \
;         __builtin_amdgcn_global_load_lds((const unsigned*)((const char*)(gbase) + (voff)[_i]), (LAS unsigned*)(lds + (bufoff) + ldsw + _i * 8192), 16, 0, 0); } while (0)
; #define PG8_LDA(dst, b, h) do { _Pragma("unroll") for (int m = 0; m < 4; ++m) _Pragma("unroll") for (int k = 0; k < 2; ++k) dst[m][k] = *(const LAS bf16x8*)(lds + PG8_SA(b, h) + aoff + m * 2048 + k * 1024); } while (0)
; #define PG8_MMA(ai, bj, At, Bt) do { __builtin_amdgcn_s_setprio(1); _Pragma("unroll") for (int m = 0; m < 4; ++m) _Pragma("unroll") for (int n = 0; n < 2; ++n) _Pragma("unroll") for (int k = 0; k < 2; ++k) \
;         acc[ai][bj][m][n] = __builtin_amdgcn_mfma_f32_16x16x32_bf16(Bt[n][k], At[m][k], acc[ai][bj][m][n], 0, 0, 0); __builtin_amdgcn_s_setprio(0); } while (0)
; #define PG8_WAIT_V(n) asm volatile("s_waitcnt vmcnt(" #n ")" ::: "memory")
; #define PG8_WAIT_L(n) asm volatile("s_waitcnt lgkmcnt(" #n ")" ::: "memory")
; #define PG8_BAR __builtin_amdgcn_s_barrier()
; #define PG8_SCHED __builtin_amdgcn_sched_barrier(0)
; __device__ __forceinline__ void gemm_phase(LAS unsigned char* lds, const GemmD g, const Sched& S, const Epi& E) {
;     ...
;             PG8_WAIT_V(8); PG8_WAIT_L(0); PG8_BAR; PG8_MMA(0, 0, At, B0); PG8_MMA(0, 1, At, B1); PG8_BAR; PG8_SCHED;
;             PG8_LDA(At, 1, 1); PG8_STAGE(PG8_SB(1, 0), b3, voffB); PG8_STAGE(PG8_SB(1, 1), b3 + hstepB, voffB); PG8_STAGE(PG8_SA(1, 0), a3, voffA);
;             PG8_WAIT_V(8); PG8_WAIT_L(0); PG8_BAR; PG8_MMA(1, 0, At, B0); PG8_MMA(1, 1, At, B1); PG8_BAR; PG8_SCHED;
;         }
;         if (wr == 0) PG8_BAR;
;         epi_run(E, acc, cur, wr, wc, fr, fq);
;         if (!has_next) break;
	s_waitcnt lgkmcnt(0)
	v_mfma_f32_16x16x32_bf16 v[126:129], v[130:133], v[182:185], v[126:129]
	v_mfma_f32_16x16x32_bf16 v[122:125], v[150:153], v[182:185], v[122:125]
	v_mfma_f32_16x16x32_bf16 v[110:113], v[130:133], v[190:193], v[110:113]
	v_mfma_f32_16x16x32_bf16 v[106:109], v[150:153], v[190:193], v[106:109]
	v_mfma_f32_16x16x32_bf16 v[94:97], v[130:133], v[220:223], v[94:97]
	v_mfma_f32_16x16x32_bf16 v[90:93], v[150:153], v[220:223], v[90:93]
	v_mfma_f32_16x16x32_bf16 v[78:81], v[130:133], v[228:231], v[78:81]
	v_mfma_f32_16x16x32_bf16 v[74:77], v[150:153], v[228:231], v[74:77]
	v_mfma_f32_16x16x32_bf16 v[126:129], v[146:149], v[186:189], v[126:129]
	v_mfma_f32_16x16x32_bf16 v[122:125], v[154:157], v[186:189], v[122:125]
	v_mfma_f32_16x16x32_bf16 v[110:113], v[146:149], v[216:219], v[110:113]
	v_mfma_f32_16x16x32_bf16 v[106:109], v[154:157], v[216:219], v[106:109]
	v_mfma_f32_16x16x32_bf16 v[94:97], v[146:149], v[224:227], v[94:97]
	v_mfma_f32_16x16x32_bf16 v[90:93], v[154:157], v[224:227], v[90:93]
	v_mfma_f32_16x16x32_bf16 v[78:81], v[146:149], v[236:239], v[78:81]
	v_mfma_f32_16x16x32_bf16 v[74:77], v[154:157], v[236:239], v[74:77]
	v_mfma_f32_16x16x32_bf16 v[118:121], v[162:165], v[182:185], v[118:121]
	v_mfma_f32_16x16x32_bf16 v[114:117], v[170:173], v[182:185], v[114:117]
	v_mfma_f32_16x16x32_bf16 v[102:105], v[162:165], v[190:193], v[102:105]
	v_mfma_f32_16x16x32_bf16 v[98:101], v[170:173], v[190:193], v[98:101]
	v_mfma_f32_16x16x32_bf16 v[86:89], v[162:165], v[220:223], v[86:89]
	v_mfma_f32_16x16x32_bf16 v[82:85], v[170:173], v[220:223], v[82:85]
	v_mfma_f32_16x16x32_bf16 v[70:73], v[162:165], v[228:231], v[70:73]
	v_mfma_f32_16x16x32_bf16 v[66:69], v[170:173], v[228:231], v[66:69]
	v_mfma_f32_16x16x32_bf16 v[118:121], v[166:169], v[186:189], v[118:121]
	v_mfma_f32_16x16x32_bf16 v[114:117], v[174:177], v[186:189], v[114:117]
	v_mfma_f32_16x16x32_bf16 v[102:105], v[166:169], v[216:219], v[102:105]
	v_mfma_f32_16x16x32_bf16 v[98:101], v[174:177], v[216:219], v[98:101]
	v_mfma_f32_16x16x32_bf16 v[86:89], v[166:169], v[224:227], v[86:89]
	v_mfma_f32_16x16x32_bf16 v[82:85], v[174:177], v[224:227], v[82:85]
	v_mfma_f32_16x16x32_bf16 v[70:73], v[166:169], v[236:239], v[70:73]
	v_mfma_f32_16x16x32_bf16 v[66:69], v[174:177], v[236:239], v[66:69]
	s_barrier
	s_add_i32 s22, s22, s30
	v_lshl_add_u64 v[178:179], v[178:179], 0, s[84:85]
	s_mov_b32 m0, s22
	ds_read_b128 v[182:185], v161 offset:49152
	ds_read_b128 v[186:189], v161 offset:50176
	ds_read_b128 v[190:193], v161 offset:51200
	ds_read_b128 v[216:219], v161 offset:52224
	ds_read_b128 v[220:223], v161 offset:53248
	ds_read_b128 v[224:227], v161 offset:54272
	ds_read_b128 v[228:231], v161 offset:55296
	ds_read_b128 v[236:239], v161 offset:56320
	global_load_lds_dwordx4 v[178:179], off
	v_lshl_add_u64 v[178:179], v[194:195], 0, s[84:85]
	s_add_i32 m0, s22, 0x2000
	s_add_i32 s22, s23, s30
	global_load_lds_dwordx4 v[178:179], off
	v_lshl_add_u64 v[178:179], v[240:241], 0, s[84:85]
	s_mov_b32 m0, s22
	s_nop 0
	global_load_lds_dwordx4 v[178:179], off
	v_lshl_add_u64 v[178:179], v[242:243], 0, s[84:85]
	s_add_i32 m0, s22, 0x2000
	s_nop 0
	global_load_lds_dwordx4 v[178:179], off
	v_lshl_add_u64 v[178:179], v[244:245], 0, s[84:85]
	s_mov_b32 m0, s18
	s_nop 0
	global_load_lds_dwordx4 v[178:179], off
	v_lshl_add_u64 v[178:179], v[246:247], 0, s[84:85]
	s_mov_b32 m0, s19
	s_nop 0
	global_load_lds_dwordx4 v[178:179], off
	s_waitcnt vmcnt(8)
	s_waitcnt lgkmcnt(0)
	s_barrier
	s_waitcnt lgkmcnt(0)
	v_mfma_f32_16x16x32_bf16 v[62:65], v[130:133], v[182:185], v[62:65]
	v_mfma_f32_16x16x32_bf16 v[58:61], v[150:153], v[182:185], v[58:61]
	v_mfma_f32_16x16x32_bf16 v[46:49], v[130:133], v[190:193], v[46:49]
	v_mfma_f32_16x16x32_bf16 v[42:45], v[150:153], v[190:193], v[42:45]
	v_mfma_f32_16x16x32_bf16 v[30:33], v[130:133], v[220:223], v[30:33]
	v_mfma_f32_16x16x32_bf16 v[26:29], v[150:153], v[220:223], v[26:29]
	v_mfma_f32_16x16x32_bf16 v[14:17], v[130:133], v[228:231], v[14:17]
	v_mfma_f32_16x16x32_bf16 v[10:13], v[150:153], v[228:231], v[10:13]
	v_mfma_f32_16x16x32_bf16 v[62:65], v[146:149], v[186:189], v[62:65]
	v_mfma_f32_16x16x32_bf16 v[58:61], v[154:157], v[186:189], v[58:61]
	v_mfma_f32_16x16x32_bf16 v[46:49], v[146:149], v[216:219], v[46:49]
	v_mfma_f32_16x16x32_bf16 v[42:45], v[154:157], v[216:219], v[42:45]
	v_mfma_f32_16x16x32_bf16 v[30:33], v[146:149], v[224:227], v[30:33]
	v_mfma_f32_16x16x32_bf16 v[26:29], v[154:157], v[224:227], v[26:29]
	v_mfma_f32_16x16x32_bf16 v[14:17], v[146:149], v[236:239], v[14:17]
	v_mfma_f32_16x16x32_bf16 v[10:13], v[154:157], v[236:239], v[10:13]
	v_mfma_f32_16x16x32_bf16 v[54:57], v[162:165], v[182:185], v[54:57]
	v_mfma_f32_16x16x32_bf16 v[50:53], v[170:173], v[182:185], v[50:53]
	v_mfma_f32_16x16x32_bf16 v[38:41], v[162:165], v[190:193], v[38:41]
	v_mfma_f32_16x16x32_bf16 v[34:37], v[170:173], v[190:193], v[34:37]
	v_mfma_f32_16x16x32_bf16 v[22:25], v[162:165], v[220:223], v[22:25]
	v_mfma_f32_16x16x32_bf16 v[18:21], v[170:173], v[220:223], v[18:21]
	v_mfma_f32_16x16x32_bf16 v[6:9], v[162:165], v[228:231], v[6:9]
	v_mfma_f32_16x16x32_bf16 v[2:5], v[170:173], v[228:231], v[2:5]
	v_mfma_f32_16x16x32_bf16 v[54:57], v[166:169], v[186:189], v[54:57]
	v_mfma_f32_16x16x32_bf16 v[50:53], v[174:177], v[186:189], v[50:53]
	v_mfma_f32_16x16x32_bf16 v[38:41], v[166:169], v[216:219], v[38:41]
	v_mfma_f32_16x16x32_bf16 v[34:37], v[174:177], v[216:219], v[34:37]
	v_mfma_f32_16x16x32_bf16 v[22:25], v[166:169], v[224:227], v[22:25]
	v_mfma_f32_16x16x32_bf16 v[18:21], v[174:177], v[224:227], v[18:21]
	v_mfma_f32_16x16x32_bf16 v[6:9], v[166:169], v[236:239], v[6:9]
	v_mfma_f32_16x16x32_bf16 v[2:5], v[174:177], v[236:239], v[2:5]
	s_barrier
	s_add_u32 s8, s8, 0x100
	s_addc_u32 s9, s9, 0
	s_add_u32 s34, s34, 0x100
	s_addc_u32 s35, s35, 0
	s_cmp_ge_u32 s92, s12
	s_mov_b32 s26, s92
	s_cbranch_scc0 .LBB0_215
	s_setprio 0
	v_readlane_b32 s8, v250, 24
	v_readlane_b32 s9, v250, 25
	s_and_b64 vcc, exec, s[8:9]
	s_cbranch_vccz .LBB0_219
	s_barrier
	s_cmp_lt_i32 s96, 4
	s_mov_b64 s[8:9], -1
	s_cbranch_scc0 .LBB0_220

; template <bool COOP>
; __global__ void __launch_bounds__(512, 2) fwd_kernel(Params p) {
;     ...
;     }
; }
.LBB0_641:
	s_nop 0
	s_nop 0
	s_nop 0
	s_nop 0
	s_nop 0
	s_nop 0
	s_nop 0
	s_nop 0
	s_nop 0
	s_nop 0
	s_nop 0
	s_endpgm
